# v42
# baseline (speedup 1.0000x reference)
.LBB0_386:
	v_ashrrev_i32_e32 v10, 9, v4
	v_and_b32_e32 v38, -16, v10
	s_mov_b32 s2, 0xfff80
	v_or_b32_e32 v10, v38, v50
	v_and_or_b32 v5, v52, s2, v6
	v_ashrrev_i32_e32 v11, 31, v10
	v_lshlrev_b64 v[12:13], 21, v[10:11]
	v_lshlrev_b32_e32 v5, 1, v5
	v_or_b32_e32 v12, v12, v5
	v_lshl_add_u64 v[14:15], s[60:61], 0, v[12:13]
	v_lshl_add_u64 v[12:13], s[62:63], 0, v[12:13]
	global_load_dwordx2 v[40:41], v[14:15], off
	global_load_dwordx2 v[42:43], v[12:13], off
	v_or_b32_e32 v12, 2, v10
	v_ashrrev_i32_e32 v13, 31, v12
	v_lshlrev_b64 v[12:13], 21, v[12:13]
	v_or_b32_e32 v12, v12, v5
	v_lshl_add_u64 v[14:15], s[60:61], 0, v[12:13]
	v_lshl_add_u64 v[12:13], s[62:63], 0, v[12:13]
	global_load_dwordx2 v[34:35], v[14:15], off
	global_load_dwordx2 v[36:37], v[12:13], off
	v_or_b32_e32 v12, 4, v10
	v_ashrrev_i32_e32 v13, 31, v12
	v_lshlrev_b64 v[12:13], 21, v[12:13]
	v_or_b32_e32 v12, v12, v5
	v_lshl_add_u64 v[14:15], s[60:61], 0, v[12:13]
	v_lshl_add_u64 v[12:13], s[62:63], 0, v[12:13]
	global_load_dwordx2 v[30:31], v[14:15], off
	global_load_dwordx2 v[32:33], v[12:13], off
	v_or_b32_e32 v12, 6, v10
	v_ashrrev_i32_e32 v13, 31, v12
	v_lshlrev_b64 v[12:13], 21, v[12:13]
	v_or_b32_e32 v12, v12, v5
	v_lshl_add_u64 v[14:15], s[60:61], 0, v[12:13]
	v_lshl_add_u64 v[12:13], s[62:63], 0, v[12:13]
	global_load_dwordx2 v[26:27], v[14:15], off
	global_load_dwordx2 v[28:29], v[12:13], off
	v_or_b32_e32 v12, 8, v10
	v_ashrrev_i32_e32 v13, 31, v12
	v_lshlrev_b64 v[12:13], 21, v[12:13]
	v_or_b32_e32 v12, v12, v5
	v_lshl_add_u64 v[14:15], s[60:61], 0, v[12:13]
	v_lshl_add_u64 v[12:13], s[62:63], 0, v[12:13]
	global_load_dwordx2 v[22:23], v[14:15], off
	global_load_dwordx2 v[24:25], v[12:13], off
	v_or_b32_e32 v12, 10, v10
	v_ashrrev_i32_e32 v13, 31, v12
	v_or_b32_e32 v10, 12, v10
	v_lshlrev_b64 v[12:13], 21, v[12:13]
	v_ashrrev_i32_e32 v11, 31, v10
	v_or_b32_e32 v12, v12, v5
	v_lshlrev_b64 v[10:11], 21, v[10:11]
	v_lshl_add_u64 v[14:15], s[60:61], 0, v[12:13]
	v_lshl_add_u64 v[12:13], s[62:63], 0, v[12:13]
	v_or_b32_e32 v10, v10, v5
	global_load_dwordx2 v[18:19], v[14:15], off
	global_load_dwordx2 v[20:21], v[12:13], off
	v_lshl_add_u64 v[12:13], s[60:61], 0, v[10:11]
	v_lshl_add_u64 v[10:11], s[62:63], 0, v[10:11]
	global_load_dwordx2 v[14:15], v[12:13], off
	global_load_dwordx2 v[16:17], v[10:11], off
	v_or_b32_e32 v10, v38, v51
	v_ashrrev_i32_e32 v11, 31, v10
	v_lshlrev_b64 v[12:13], 21, v[10:11]
	v_or_b32_e32 v12, v12, v5
	v_ashrrev_i32_e32 v5, 31, v4
	v_lshlrev_b64 v[38:39], 12, v[4:5]
	v_lshl_add_u64 v[10:11], s[60:61], 0, v[12:13]
	v_lshl_add_u64 v[12:13], s[62:63], 0, v[12:13]
	global_load_dwordx2 v[10:11], v[10:11], off
	v_lshl_add_u64 v[38:39], v[8:9], 0, v[38:39]
	global_load_dwordx2 v[12:13], v[12:13], off
	v_add_u32_e32 v4, s66, v4
	v_add_u32_e32 v52, s31, v52
	s_waitcnt vmcnt(15)
	v_lshlrev_b32_e32 v5, 16, v40
	s_waitcnt vmcnt(14)
	v_lshlrev_b32_e32 v53, 16, v42
	v_and_b32_e32 v40, 0xffff0000, v40
	v_and_b32_e32 v42, 0xffff0000, v42
	v_fma_f32 v5, -v49, v53, v5
	v_fma_f32 v40, -v49, v42, v40
	v_lshlrev_b32_e32 v42, 16, v41
	v_lshlrev_b32_e32 v53, 16, v43
	v_and_b32_e32 v41, 0xffff0000, v41
	v_and_b32_e32 v43, 0xffff0000, v43
	v_fma_f32 v41, -v49, v43, v41
	v_fma_f32 v42, -v49, v53, v42
	v_mul_f32_e32 v43, v40, v40
	v_mul_f32_e32 v53, v41, v41
	v_fmac_f32_e32 v43, v5, v5
	v_fmac_f32_e32 v53, v42, v42
	v_add_f32_e32 v43, v43, v53
	s_nop 1
	v_add_f32_dpp v43, v43, v43 quad_perm:[1,0,3,2] row_mask:0xf bank_mask:0xf
	s_nop 1
	v_add_f32_dpp v43, v43, v43 quad_perm:[2,3,0,1] row_mask:0xf bank_mask:0xf
	s_nop 1
	v_add_f32_dpp v43, v43, v43 row_half_mirror row_mask:0xf bank_mask:0xf
	s_nop 1
	v_add_f32_dpp v43, v43, v43 row_mirror row_mask:0xf bank_mask:0xf
	v_mov_b32_e32 v53, v43
	s_nop 1
	v_permlane16_swap_b32_e32 v43, v53
	v_add_f32_e32 v43, v43, v53
	v_mov_b32_e32 v53, v43
	s_nop 1
	v_permlane32_swap_b32_e32 v43, v53
	v_add_f32_e32 v43, v43, v53
	v_fmamk_f32 v43, v43, 0x3b800000, v198
	v_cmp_gt_f32_e32 vcc, s40, v43
	v_mul_f32_e32 v53, 0x4b800000, v43
	s_nop 0
	v_cndmask_b32_e32 v43, v43, v53, vcc
	v_rsq_f32_e32 v43, v43
	s_nop 0
	v_mul_f32_e32 v53, 0x45800000, v43
	v_cndmask_b32_e32 v43, v43, v53, vcc
	v_mul_f32_e32 v43, 0x3f24fd5c, v43
	v_mul_f32_e32 v5, v5, v43
	v_mul_f32_e32 v40, v40, v43
	v_mul_f32_e32 v5, v0, v5
	v_mul_f32_e32 v40, v1, v40
	s_nop 0
	v_cvt_pk_bf16_f32 v40, v5, v40
	v_mul_f32_e32 v5, v42, v43
	v_mul_f32_e32 v41, v41, v43
	v_mul_f32_e32 v5, v2, v5
	v_mul_f32_e32 v41, v3, v41
	s_nop 0
	v_cvt_pk_bf16_f32 v41, v5, v41
	global_store_dwordx2 v[38:39], v[40:41], off
	s_waitcnt vmcnt(14)
	v_lshlrev_b32_e32 v5, 16, v34
	s_waitcnt vmcnt(13)
	v_lshlrev_b32_e32 v40, 16, v36
	v_and_b32_e32 v34, 0xffff0000, v34
	v_and_b32_e32 v36, 0xffff0000, v36
	v_fma_f32 v5, -v49, v40, v5
	v_fma_f32 v34, -v49, v36, v34
	v_lshlrev_b32_e32 v36, 16, v35
	v_lshlrev_b32_e32 v40, 16, v37
	v_and_b32_e32 v35, 0xffff0000, v35
	v_and_b32_e32 v37, 0xffff0000, v37
	v_fma_f32 v35, -v49, v37, v35
	v_fma_f32 v36, -v49, v40, v36
	v_mul_f32_e32 v37, v34, v34
	v_mul_f32_e32 v40, v35, v35
	v_fmac_f32_e32 v37, v5, v5
	v_fmac_f32_e32 v40, v36, v36
	v_add_f32_e32 v37, v37, v40
	s_nop 1
	v_add_f32_dpp v37, v37, v37 quad_perm:[1,0,3,2] row_mask:0xf bank_mask:0xf
	s_nop 1
	v_add_f32_dpp v37, v37, v37 quad_perm:[2,3,0,1] row_mask:0xf bank_mask:0xf
	s_nop 1
	v_add_f32_dpp v37, v37, v37 row_half_mirror row_mask:0xf bank_mask:0xf
	s_nop 1
	v_add_f32_dpp v37, v37, v37 row_mirror row_mask:0xf bank_mask:0xf
	v_mov_b32_e32 v40, v37
	s_nop 1
	v_permlane16_swap_b32_e32 v37, v40
	v_add_f32_e32 v37, v37, v40
	v_mov_b32_e32 v40, v37
	s_nop 1
	v_permlane32_swap_b32_e32 v37, v40
	v_add_f32_e32 v37, v37, v40
	v_fmamk_f32 v37, v37, 0x3b800000, v198
	v_cmp_gt_f32_e32 vcc, s40, v37
	v_mul_f32_e32 v40, 0x4b800000, v37
	s_nop 0
	v_cndmask_b32_e32 v37, v37, v40, vcc
	v_rsq_f32_e32 v37, v37
	s_nop 0
	v_mul_f32_e32 v40, 0x45800000, v37
	v_cndmask_b32_e32 v37, v37, v40, vcc
	v_mul_f32_e32 v37, 0x3f24fd5c, v37
	v_mul_f32_e32 v5, v5, v37
	v_mul_f32_e32 v34, v34, v37
	v_mul_f32_e32 v5, v0, v5
	v_mul_f32_e32 v34, v1, v34
	s_nop 0
	v_cvt_pk_bf16_f32 v34, v5, v34
	v_mul_f32_e32 v5, v36, v37
	v_mul_f32_e32 v35, v35, v37
	v_mul_f32_e32 v5, v2, v5
	v_mul_f32_e32 v35, v3, v35
	s_nop 0
	v_cvt_pk_bf16_f32 v35, v5, v35
	global_store_dwordx2 v[38:39], v[34:35], off offset:512
	s_waitcnt vmcnt(13)
	v_lshlrev_b32_e32 v5, 16, v30
	s_waitcnt vmcnt(12)
	v_lshlrev_b32_e32 v34, 16, v32
	v_and_b32_e32 v30, 0xffff0000, v30
	v_and_b32_e32 v32, 0xffff0000, v32
	v_fma_f32 v5, -v49, v34, v5
	v_fma_f32 v30, -v49, v32, v30
	v_lshlrev_b32_e32 v32, 16, v31
	v_lshlrev_b32_e32 v34, 16, v33
	v_and_b32_e32 v31, 0xffff0000, v31
	v_and_b32_e32 v33, 0xffff0000, v33
	v_fma_f32 v31, -v49, v33, v31
	v_fma_f32 v32, -v49, v34, v32
	v_mul_f32_e32 v33, v30, v30
	v_mul_f32_e32 v34, v31, v31
	v_fmac_f32_e32 v33, v5, v5
	v_fmac_f32_e32 v34, v32, v32
	v_add_f32_e32 v33, v33, v34
	s_nop 1
	v_add_f32_dpp v33, v33, v33 quad_perm:[1,0,3,2] row_mask:0xf bank_mask:0xf
	s_nop 1
	v_add_f32_dpp v33, v33, v33 quad_perm:[2,3,0,1] row_mask:0xf bank_mask:0xf
	s_nop 1
	v_add_f32_dpp v33, v33, v33 row_half_mirror row_mask:0xf bank_mask:0xf
	s_nop 1
	v_add_f32_dpp v33, v33, v33 row_mirror row_mask:0xf bank_mask:0xf
	v_mov_b32_e32 v34, v33
	s_nop 1
	v_permlane16_swap_b32_e32 v33, v34
	v_add_f32_e32 v33, v33, v34
	v_mov_b32_e32 v34, v33
	s_nop 1
	v_permlane32_swap_b32_e32 v33, v34
	v_add_f32_e32 v33, v33, v34
	v_fmamk_f32 v33, v33, 0x3b800000, v198
	v_cmp_gt_f32_e32 vcc, s40, v33
	v_mul_f32_e32 v34, 0x4b800000, v33
	s_nop 0
	v_cndmask_b32_e32 v33, v33, v34, vcc
	v_rsq_f32_e32 v33, v33
	s_nop 0
	v_mul_f32_e32 v34, 0x45800000, v33
	v_cndmask_b32_e32 v33, v33, v34, vcc
	v_mul_f32_e32 v33, 0x3f24fd5c, v33
	v_mul_f32_e32 v5, v5, v33
	v_mul_f32_e32 v30, v30, v33
	v_mul_f32_e32 v5, v0, v5
	v_mul_f32_e32 v30, v1, v30
	s_nop 0
	v_cvt_pk_bf16_f32 v30, v5, v30
	v_mul_f32_e32 v5, v32, v33
	v_mul_f32_e32 v31, v31, v33
	v_mul_f32_e32 v5, v2, v5
	v_mul_f32_e32 v31, v3, v31
	s_nop 0
	v_cvt_pk_bf16_f32 v31, v5, v31
	global_store_dwordx2 v[38:39], v[30:31], off offset:1024
	s_waitcnt vmcnt(12)
	v_lshlrev_b32_e32 v5, 16, v26
	s_waitcnt vmcnt(11)
	v_lshlrev_b32_e32 v30, 16, v28
	v_and_b32_e32 v26, 0xffff0000, v26
	v_and_b32_e32 v28, 0xffff0000, v28
	v_fma_f32 v5, -v49, v30, v5
	v_fma_f32 v26, -v49, v28, v26
	v_lshlrev_b32_e32 v28, 16, v27
	v_lshlrev_b32_e32 v30, 16, v29
	v_and_b32_e32 v27, 0xffff0000, v27
	v_and_b32_e32 v29, 0xffff0000, v29
	v_fma_f32 v27, -v49, v29, v27
	v_fma_f32 v28, -v49, v30, v28
	v_mul_f32_e32 v29, v26, v26
	v_mul_f32_e32 v30, v27, v27
	v_fmac_f32_e32 v29, v5, v5
	v_fmac_f32_e32 v30, v28, v28
	v_add_f32_e32 v29, v29, v30
	s_nop 1
	v_add_f32_dpp v29, v29, v29 quad_perm:[1,0,3,2] row_mask:0xf bank_mask:0xf
	s_nop 1
	v_add_f32_dpp v29, v29, v29 quad_perm:[2,3,0,1] row_mask:0xf bank_mask:0xf
	s_nop 1
	v_add_f32_dpp v29, v29, v29 row_half_mirror row_mask:0xf bank_mask:0xf
	s_nop 1
	v_add_f32_dpp v29, v29, v29 row_mirror row_mask:0xf bank_mask:0xf
	v_mov_b32_e32 v30, v29
	s_nop 1
	v_permlane16_swap_b32_e32 v29, v30
	v_add_f32_e32 v29, v29, v30
	v_mov_b32_e32 v30, v29
	s_nop 1
	v_permlane32_swap_b32_e32 v29, v30
	v_add_f32_e32 v29, v29, v30
	v_fmamk_f32 v29, v29, 0x3b800000, v198
	v_cmp_gt_f32_e32 vcc, s40, v29
	v_mul_f32_e32 v30, 0x4b800000, v29
	s_nop 0
	v_cndmask_b32_e32 v29, v29, v30, vcc
	v_rsq_f32_e32 v29, v29
	s_nop 0
	v_mul_f32_e32 v30, 0x45800000, v29
	v_cndmask_b32_e32 v29, v29, v30, vcc
	v_mul_f32_e32 v29, 0x3f24fd5c, v29
	v_mul_f32_e32 v5, v5, v29
	v_mul_f32_e32 v26, v26, v29
	v_mul_f32_e32 v5, v0, v5
	v_mul_f32_e32 v26, v1, v26
	s_nop 0
	v_cvt_pk_bf16_f32 v26, v5, v26
	v_mul_f32_e32 v5, v28, v29
	v_mul_f32_e32 v27, v27, v29
	v_mul_f32_e32 v5, v2, v5
	v_mul_f32_e32 v27, v3, v27
	s_nop 0
	v_cvt_pk_bf16_f32 v27, v5, v27
	global_store_dwordx2 v[38:39], v[26:27], off offset:1536
	s_waitcnt vmcnt(11)
	v_lshlrev_b32_e32 v5, 16, v22
	s_waitcnt vmcnt(10)
	v_lshlrev_b32_e32 v26, 16, v24
	v_and_b32_e32 v22, 0xffff0000, v22
	v_and_b32_e32 v24, 0xffff0000, v24
	v_fma_f32 v5, -v49, v26, v5
	v_fma_f32 v22, -v49, v24, v22
	v_lshlrev_b32_e32 v24, 16, v23
	v_lshlrev_b32_e32 v26, 16, v25
	v_and_b32_e32 v23, 0xffff0000, v23
	v_and_b32_e32 v25, 0xffff0000, v25
	v_fma_f32 v23, -v49, v25, v23
	v_fma_f32 v24, -v49, v26, v24
	v_mul_f32_e32 v25, v22, v22
	v_mul_f32_e32 v26, v23, v23
	v_fmac_f32_e32 v25, v5, v5
	v_fmac_f32_e32 v26, v24, v24
	v_add_f32_e32 v25, v25, v26
	s_nop 1
	v_add_f32_dpp v25, v25, v25 quad_perm:[1,0,3,2] row_mask:0xf bank_mask:0xf
	s_nop 1
	v_add_f32_dpp v25, v25, v25 quad_perm:[2,3,0,1] row_mask:0xf bank_mask:0xf
	s_nop 1
	v_add_f32_dpp v25, v25, v25 row_half_mirror row_mask:0xf bank_mask:0xf
	s_nop 1
	v_add_f32_dpp v25, v25, v25 row_mirror row_mask:0xf bank_mask:0xf
	v_mov_b32_e32 v26, v25
	s_nop 1
	v_permlane16_swap_b32_e32 v25, v26
	v_add_f32_e32 v25, v25, v26
	v_mov_b32_e32 v26, v25
	s_nop 1
	v_permlane32_swap_b32_e32 v25, v26
	v_add_f32_e32 v25, v25, v26
	v_fmamk_f32 v25, v25, 0x3b800000, v198
	v_cmp_gt_f32_e32 vcc, s40, v25
	v_mul_f32_e32 v26, 0x4b800000, v25
	s_nop 0
	v_cndmask_b32_e32 v25, v25, v26, vcc
	v_rsq_f32_e32 v25, v25
	s_nop 0
	v_mul_f32_e32 v26, 0x45800000, v25
	v_cndmask_b32_e32 v25, v25, v26, vcc
	v_mul_f32_e32 v25, 0x3f24fd5c, v25
	v_mul_f32_e32 v5, v5, v25
	v_mul_f32_e32 v22, v22, v25
	v_mul_f32_e32 v5, v0, v5
	v_mul_f32_e32 v22, v1, v22
	s_nop 0
	v_cvt_pk_bf16_f32 v22, v5, v22
	v_mul_f32_e32 v5, v24, v25
	v_mul_f32_e32 v23, v23, v25
	v_mul_f32_e32 v5, v2, v5
	v_mul_f32_e32 v23, v3, v23
	s_nop 0
	v_cvt_pk_bf16_f32 v23, v5, v23
	global_store_dwordx2 v[38:39], v[22:23], off offset:2048
	s_waitcnt vmcnt(10)
	v_lshlrev_b32_e32 v5, 16, v18
	s_waitcnt vmcnt(9)
	v_lshlrev_b32_e32 v22, 16, v20
	v_and_b32_e32 v18, 0xffff0000, v18
	v_and_b32_e32 v20, 0xffff0000, v20
	v_fma_f32 v5, -v49, v22, v5
	v_fma_f32 v18, -v49, v20, v18
	v_lshlrev_b32_e32 v20, 16, v19
	v_lshlrev_b32_e32 v22, 16, v21
	v_and_b32_e32 v19, 0xffff0000, v19
	v_and_b32_e32 v21, 0xffff0000, v21
	v_fma_f32 v19, -v49, v21, v19
	v_fma_f32 v20, -v49, v22, v20
	v_mul_f32_e32 v21, v18, v18
	v_mul_f32_e32 v22, v19, v19
	v_fmac_f32_e32 v21, v5, v5
	v_fmac_f32_e32 v22, v20, v20
	v_add_f32_e32 v21, v21, v22
	s_nop 1
	v_add_f32_dpp v21, v21, v21 quad_perm:[1,0,3,2] row_mask:0xf bank_mask:0xf
	s_nop 1
	v_add_f32_dpp v21, v21, v21 quad_perm:[2,3,0,1] row_mask:0xf bank_mask:0xf
	s_nop 1
	v_add_f32_dpp v21, v21, v21 row_half_mirror row_mask:0xf bank_mask:0xf
	s_nop 1
	v_add_f32_dpp v21, v21, v21 row_mirror row_mask:0xf bank_mask:0xf
	v_mov_b32_e32 v22, v21
	s_nop 1
	v_permlane16_swap_b32_e32 v21, v22
	v_add_f32_e32 v21, v21, v22
	v_mov_b32_e32 v22, v21
	s_nop 1
	v_permlane32_swap_b32_e32 v21, v22
	v_add_f32_e32 v21, v21, v22
	v_fmamk_f32 v21, v21, 0x3b800000, v198
	v_cmp_gt_f32_e32 vcc, s40, v21
	v_mul_f32_e32 v22, 0x4b800000, v21
	s_nop 0
	v_cndmask_b32_e32 v21, v21, v22, vcc
	v_rsq_f32_e32 v21, v21
	s_nop 0
	v_mul_f32_e32 v22, 0x45800000, v21
	v_cndmask_b32_e32 v21, v21, v22, vcc
	v_mul_f32_e32 v21, 0x3f24fd5c, v21
	v_mul_f32_e32 v5, v5, v21
	v_mul_f32_e32 v18, v18, v21
	v_mul_f32_e32 v5, v0, v5
	v_mul_f32_e32 v18, v1, v18
	s_nop 0
	v_cvt_pk_bf16_f32 v18, v5, v18
	v_mul_f32_e32 v5, v20, v21
	v_mul_f32_e32 v19, v19, v21
	v_mul_f32_e32 v5, v2, v5
	v_mul_f32_e32 v19, v3, v19
	s_nop 0
	v_cvt_pk_bf16_f32 v19, v5, v19
	global_store_dwordx2 v[38:39], v[18:19], off offset:2560
	s_waitcnt vmcnt(9)
	v_lshlrev_b32_e32 v5, 16, v14
	s_waitcnt vmcnt(8)
	v_lshlrev_b32_e32 v18, 16, v16
	v_and_b32_e32 v14, 0xffff0000, v14
	v_and_b32_e32 v16, 0xffff0000, v16
	v_fma_f32 v5, -v49, v18, v5
	v_fma_f32 v14, -v49, v16, v14
	v_lshlrev_b32_e32 v16, 16, v15
	v_lshlrev_b32_e32 v18, 16, v17
	v_and_b32_e32 v15, 0xffff0000, v15
	v_and_b32_e32 v17, 0xffff0000, v17
	v_fma_f32 v15, -v49, v17, v15
	v_fma_f32 v16, -v49, v18, v16
	v_mul_f32_e32 v17, v14, v14
	v_mul_f32_e32 v18, v15, v15
	v_fmac_f32_e32 v17, v5, v5
	v_fmac_f32_e32 v18, v16, v16
	v_add_f32_e32 v17, v17, v18
	s_nop 1
	v_add_f32_dpp v17, v17, v17 quad_perm:[1,0,3,2] row_mask:0xf bank_mask:0xf
	s_nop 1
	v_add_f32_dpp v17, v17, v17 quad_perm:[2,3,0,1] row_mask:0xf bank_mask:0xf
	s_nop 1
	v_add_f32_dpp v17, v17, v17 row_half_mirror row_mask:0xf bank_mask:0xf
	s_nop 1
	v_add_f32_dpp v17, v17, v17 row_mirror row_mask:0xf bank_mask:0xf
	v_mov_b32_e32 v18, v17
	s_nop 1
	v_permlane16_swap_b32_e32 v17, v18
	v_add_f32_e32 v17, v17, v18
	v_mov_b32_e32 v18, v17
	s_nop 1
	v_permlane32_swap_b32_e32 v17, v18
	v_add_f32_e32 v17, v17, v18
	v_fmamk_f32 v17, v17, 0x3b800000, v198
	v_cmp_gt_f32_e32 vcc, s40, v17
	v_mul_f32_e32 v18, 0x4b800000, v17
	s_nop 0
	v_cndmask_b32_e32 v17, v17, v18, vcc
	v_rsq_f32_e32 v17, v17
	s_nop 0
	v_mul_f32_e32 v18, 0x45800000, v17
	v_cndmask_b32_e32 v17, v17, v18, vcc
	v_mul_f32_e32 v17, 0x3f24fd5c, v17
	v_mul_f32_e32 v5, v5, v17
	v_mul_f32_e32 v14, v14, v17
	v_mul_f32_e32 v5, v0, v5
	v_mul_f32_e32 v14, v1, v14
	s_nop 0
	v_cvt_pk_bf16_f32 v14, v5, v14
	v_mul_f32_e32 v5, v16, v17
	v_mul_f32_e32 v15, v15, v17
	v_mul_f32_e32 v5, v2, v5
	v_mul_f32_e32 v15, v3, v15
	s_nop 0
	v_cvt_pk_bf16_f32 v15, v5, v15
	global_store_dwordx2 v[38:39], v[14:15], off offset:3072
	s_waitcnt vmcnt(8)
	v_lshlrev_b32_e32 v5, 16, v10
	s_waitcnt vmcnt(7)
	v_lshlrev_b32_e32 v14, 16, v12
	v_and_b32_e32 v10, 0xffff0000, v10
	v_and_b32_e32 v12, 0xffff0000, v12
	v_fma_f32 v5, -v49, v14, v5
	v_fma_f32 v10, -v49, v12, v10
	v_lshlrev_b32_e32 v12, 16, v11
	v_lshlrev_b32_e32 v14, 16, v13
	v_and_b32_e32 v11, 0xffff0000, v11
	v_and_b32_e32 v13, 0xffff0000, v13
	v_fma_f32 v11, -v49, v13, v11
	v_fma_f32 v12, -v49, v14, v12
	v_mul_f32_e32 v13, v10, v10
	v_mul_f32_e32 v14, v11, v11
	v_fmac_f32_e32 v13, v5, v5
	v_fmac_f32_e32 v14, v12, v12
	v_add_f32_e32 v13, v13, v14
	s_nop 1
	v_add_f32_dpp v13, v13, v13 quad_perm:[1,0,3,2] row_mask:0xf bank_mask:0xf
	s_nop 1
	v_add_f32_dpp v13, v13, v13 quad_perm:[2,3,0,1] row_mask:0xf bank_mask:0xf
	s_nop 1
	v_add_f32_dpp v13, v13, v13 row_half_mirror row_mask:0xf bank_mask:0xf
	s_nop 1
	v_add_f32_dpp v13, v13, v13 row_mirror row_mask:0xf bank_mask:0xf
	v_mov_b32_e32 v14, v13
	s_nop 1
	v_permlane16_swap_b32_e32 v13, v14
	v_add_f32_e32 v13, v13, v14
	v_mov_b32_e32 v14, v13
	s_nop 1
	v_permlane32_swap_b32_e32 v13, v14
	v_add_f32_e32 v13, v13, v14
	v_fmamk_f32 v13, v13, 0x3b800000, v198
	v_cmp_gt_f32_e32 vcc, s40, v13
	v_mul_f32_e32 v14, 0x4b800000, v13
	s_nop 0
	v_cndmask_b32_e32 v13, v13, v14, vcc
	v_rsq_f32_e32 v13, v13
	s_nop 0
	v_mul_f32_e32 v14, 0x45800000, v13
	v_cndmask_b32_e32 v13, v13, v14, vcc
	v_mul_f32_e32 v13, 0x3f24fd5c, v13
	v_mul_f32_e32 v5, v5, v13
	v_mul_f32_e32 v10, v10, v13
	v_mul_f32_e32 v5, v0, v5
	v_mul_f32_e32 v10, v1, v10
	v_mul_f32_e32 v11, v11, v13
	v_cmp_lt_i32_e32 vcc, s41, v4
	s_nop 0
	v_cvt_pk_bf16_f32 v10, v5, v10
	v_mul_f32_e32 v5, v12, v13
	v_mul_f32_e32 v11, v3, v11
	s_or_b64 s[4:5], vcc, s[4:5]
	v_mul_f32_e32 v5, v2, v5
	s_nop 0
	v_cvt_pk_bf16_f32 v11, v5, v11
	global_store_dwordx2 v[38:39], v[10:11], off offset:3584
	s_andn2_b64 exec, exec, s[4:5]
	s_cbranch_execnz .LBB0_386
